# cache policy: nt (non-temporal) on the residual-epilogue h loads and stores (streamed once per phase), on top of v28
# baseline (speedup 1.0000x reference)
.LBB0_394:
	s_add_i32 s2, s47, 0xffffff80
	s_ashr_i32 s20, s47, 31
	s_cmpk_lt_i32 s47, 0x80
	v_readlane_b32 s52, v239, 17
	s_cselect_b32 s21, s20, 0
	s_cselect_b32 s20, s47, s2
	v_readlane_b32 s53, v239, 18
	v_readlane_b32 s56, v239, 21
	v_readlane_b32 s57, v239, 22
	s_movk_i32 s23, 0x2400
	s_cselect_b32 s2, s87, s9
	s_cselect_b32 s22, s86, s8
	s_cselect_b32 s24, s53, s57
	s_cselect_b32 s25, s52, s56
	s_cselect_b32 s26, s23, 0x4800
	s_lshl_b64 s[20:21], s[20:21], 20
	s_add_u32 s22, s22, s20
	s_addc_u32 s23, s2, s21
	s_add_u32 s20, s25, s20
	s_addc_u32 s21, s24, s21
	s_cmp_gt_i32 s47, 63
	s_cselect_b32 s2, s26, 0
	v_lshl_or_b32 v158, s48, 8, v167
	s_lshl_b32 s2, s2, 2
	s_add_u32 s24, s37, s2
	v_ashrrev_i32_e32 v159, 31, v158
	s_addc_u32 s25, s38, 0
	v_lshlrev_b64 v[158:159], 2, v[158:159]
	v_lshl_add_u64 v[160:161], s[24:25], 0, v[158:159]
	v_lshl_add_u64 v[164:165], s[20:21], 0, v[158:159]
	v_lshlrev_b64 v[180:181], 2, v[134:135]
	global_load_dwordx4 v[172:175], v[160:161], off
	global_load_dwordx4 v[176:179], v[160:161], off offset:64
	global_load_dwordx4 v[182:185], v[160:161], off offset:512
	global_load_dwordx4 v[186:189], v[160:161], off offset:576
	v_lshl_add_u64 v[244:245], s[22:23], 0, v[158:159]
	v_lshl_add_u64 v[162:163], v[164:165], 0, v[180:181]
	global_load_dwordx4 v[190:193], v[162:163], off nt
	global_load_dwordx4 v[194:197], v[162:163], off offset:64 nt
	global_load_dwordx4 v[198:201], v[162:163], off offset:512 nt
	global_load_dwordx4 v[202:205], v[162:163], off offset:576 nt
	v_lshl_add_u64 v[240:241], v[164:165], 0, v[144:145]
	global_load_dwordx4 v[206:209], v[240:241], off nt
	global_load_dwordx4 v[210:213], v[240:241], off offset:64 nt
	global_load_dwordx4 v[214:217], v[240:241], off offset:512 nt
	global_load_dwordx4 v[218:221], v[240:241], off offset:576 nt
	v_lshl_add_u64 v[242:243], v[164:165], 0, v[146:147]
	global_load_dwordx4 v[222:225], v[242:243], off nt
	global_load_dwordx4 v[226:229], v[242:243], off offset:64 nt
	global_load_dwordx4 v[230:233], v[242:243], off offset:512 nt
	global_load_dwordx4 v[234:237], v[242:243], off offset:576 nt
	s_waitcnt vmcnt(8)
	v_pk_mul_f32 v[172:173], v[172:173], 0.5 op_sel_hi:[1,0]
	v_pk_mul_f32 v[174:175], v[174:175], 0.5 op_sel_hi:[1,0]
	v_pk_mul_f32 v[176:177], v[176:177], 0.5 op_sel_hi:[1,0]
	v_pk_mul_f32 v[178:179], v[178:179], 0.5 op_sel_hi:[1,0]
	v_pk_mul_f32 v[182:183], v[182:183], 0.5 op_sel_hi:[1,0]
	v_pk_mul_f32 v[184:185], v[184:185], 0.5 op_sel_hi:[1,0]
	v_pk_mul_f32 v[186:187], v[186:187], 0.5 op_sel_hi:[1,0]
	v_pk_mul_f32 v[188:189], v[188:189], 0.5 op_sel_hi:[1,0]
	v_lshl_add_u64 v[162:163], v[244:245], 0, v[180:181]
	v_pk_fma_f32 v[190:191], v[126:127], v[172:173], v[190:191]
	v_pk_fma_f32 v[192:193], v[128:129], v[174:175], v[192:193]
	v_pk_fma_f32 v[194:195], v[122:123], v[176:177], v[194:195]
	v_pk_fma_f32 v[196:197], v[124:125], v[178:179], v[196:197]
	v_pk_fma_f32 v[198:199], v[118:119], v[182:183], v[198:199]
	v_pk_fma_f32 v[200:201], v[120:121], v[184:185], v[200:201]
	v_pk_fma_f32 v[202:203], v[106:107], v[186:187], v[202:203]
	v_pk_fma_f32 v[204:205], v[108:109], v[188:189], v[204:205]
	global_store_dwordx4 v[162:163], v[190:193], off nt
	global_store_dwordx4 v[162:163], v[194:197], off offset:64 nt
	global_store_dwordx4 v[162:163], v[198:201], off offset:512 nt
	global_store_dwordx4 v[162:163], v[202:205], off offset:576 nt
	v_lshl_add_u64 v[162:163], v[164:165], 0, v[148:149]
	global_load_dwordx4 v[190:193], v[162:163], off nt
	global_load_dwordx4 v[194:197], v[162:163], off offset:64 nt
	global_load_dwordx4 v[198:201], v[162:163], off offset:512 nt
	global_load_dwordx4 v[202:205], v[162:163], off offset:576 nt
	s_waitcnt vmcnt(12)
	v_lshl_add_u64 v[240:241], v[244:245], 0, v[144:145]
	v_pk_fma_f32 v[206:207], v[114:115], v[172:173], v[206:207]
	v_pk_fma_f32 v[208:209], v[116:117], v[174:175], v[208:209]
	v_pk_fma_f32 v[210:211], v[110:111], v[176:177], v[210:211]
	v_pk_fma_f32 v[212:213], v[112:113], v[178:179], v[212:213]
	v_pk_fma_f32 v[214:215], v[102:103], v[182:183], v[214:215]
	v_pk_fma_f32 v[216:217], v[104:105], v[184:185], v[216:217]
	v_pk_fma_f32 v[218:219], v[90:91], v[186:187], v[218:219]
	v_pk_fma_f32 v[220:221], v[92:93], v[188:189], v[220:221]
	global_store_dwordx4 v[240:241], v[206:209], off nt
	global_store_dwordx4 v[240:241], v[210:213], off offset:64 nt
	global_store_dwordx4 v[240:241], v[214:217], off offset:512 nt
	global_store_dwordx4 v[240:241], v[218:221], off offset:576 nt
	v_lshl_add_u64 v[240:241], v[164:165], 0, v[150:151]
	global_load_dwordx4 v[206:209], v[240:241], off nt
	global_load_dwordx4 v[210:213], v[240:241], off offset:64 nt
	global_load_dwordx4 v[214:217], v[240:241], off offset:512 nt
	global_load_dwordx4 v[218:221], v[240:241], off offset:576 nt
	s_waitcnt vmcnt(16)
	v_lshl_add_u64 v[242:243], v[244:245], 0, v[146:147]
	v_pk_fma_f32 v[222:223], v[98:99], v[172:173], v[222:223]
	v_pk_fma_f32 v[224:225], v[100:101], v[174:175], v[224:225]
	v_pk_fma_f32 v[226:227], v[94:95], v[176:177], v[226:227]
	v_pk_fma_f32 v[228:229], v[96:97], v[178:179], v[228:229]
	v_pk_fma_f32 v[230:231], v[86:87], v[182:183], v[230:231]
	v_pk_fma_f32 v[232:233], v[88:89], v[184:185], v[232:233]
	v_pk_fma_f32 v[234:235], v[74:75], v[186:187], v[234:235]
	v_pk_fma_f32 v[236:237], v[76:77], v[188:189], v[236:237]
	global_store_dwordx4 v[242:243], v[222:225], off nt
	global_store_dwordx4 v[242:243], v[226:229], off offset:64 nt
	global_store_dwordx4 v[242:243], v[230:233], off offset:512 nt
	global_store_dwordx4 v[242:243], v[234:237], off offset:576 nt
	v_lshl_add_u64 v[242:243], v[164:165], 0, v[152:153]
	global_load_dwordx4 v[222:225], v[242:243], off nt
	global_load_dwordx4 v[226:229], v[242:243], off offset:64 nt
	global_load_dwordx4 v[230:233], v[242:243], off offset:512 nt
	global_load_dwordx4 v[234:237], v[242:243], off offset:576 nt
	s_waitcnt vmcnt(16)
	v_lshl_add_u64 v[162:163], v[244:245], 0, v[148:149]
	v_pk_fma_f32 v[190:191], v[82:83], v[172:173], v[190:191]
	v_pk_fma_f32 v[192:193], v[84:85], v[174:175], v[192:193]
	v_pk_fma_f32 v[194:195], v[78:79], v[176:177], v[194:195]
	v_pk_fma_f32 v[196:197], v[80:81], v[178:179], v[196:197]
	v_pk_fma_f32 v[198:199], v[70:71], v[182:183], v[198:199]
	v_pk_fma_f32 v[200:201], v[72:73], v[184:185], v[200:201]
	v_pk_fma_f32 v[202:203], v[66:67], v[186:187], v[202:203]
	v_pk_fma_f32 v[204:205], v[68:69], v[188:189], v[204:205]
	global_store_dwordx4 v[162:163], v[190:193], off nt
	global_store_dwordx4 v[162:163], v[194:197], off offset:64 nt
	global_store_dwordx4 v[162:163], v[198:201], off offset:512 nt
	global_store_dwordx4 v[162:163], v[202:205], off offset:576 nt
	v_lshl_add_u64 v[162:163], v[164:165], 0, v[154:155]
	global_load_dwordx4 v[190:193], v[162:163], off nt
	global_load_dwordx4 v[194:197], v[162:163], off offset:64 nt
	global_load_dwordx4 v[198:201], v[162:163], off offset:512 nt
	global_load_dwordx4 v[202:205], v[162:163], off offset:576 nt
	s_waitcnt vmcnt(16)
	v_lshl_add_u64 v[240:241], v[244:245], 0, v[150:151]
	v_pk_fma_f32 v[206:207], v[62:63], v[172:173], v[206:207]
	v_pk_fma_f32 v[208:209], v[64:65], v[174:175], v[208:209]
	v_pk_fma_f32 v[210:211], v[58:59], v[176:177], v[210:211]
	v_pk_fma_f32 v[212:213], v[60:61], v[178:179], v[212:213]
	v_pk_fma_f32 v[214:215], v[54:55], v[182:183], v[214:215]
	v_pk_fma_f32 v[216:217], v[56:57], v[184:185], v[216:217]
	v_pk_fma_f32 v[218:219], v[42:43], v[186:187], v[218:219]
	v_pk_fma_f32 v[220:221], v[44:45], v[188:189], v[220:221]
	global_store_dwordx4 v[240:241], v[206:209], off nt
	global_store_dwordx4 v[240:241], v[210:213], off offset:64 nt
	global_store_dwordx4 v[240:241], v[214:217], off offset:512 nt
	global_store_dwordx4 v[240:241], v[218:221], off offset:576 nt
	v_lshl_add_u64 v[240:241], v[164:165], 0, v[156:157]
	global_load_dwordx4 v[206:209], v[240:241], off nt
	global_load_dwordx4 v[210:213], v[240:241], off offset:64 nt
	global_load_dwordx4 v[214:217], v[240:241], off offset:512 nt
	global_load_dwordx4 v[218:221], v[240:241], off offset:576 nt
	s_waitcnt vmcnt(16)
	v_lshl_add_u64 v[242:243], v[244:245], 0, v[152:153]
	v_pk_fma_f32 v[222:223], v[50:51], v[172:173], v[222:223]
	v_pk_fma_f32 v[224:225], v[52:53], v[174:175], v[224:225]
	v_pk_fma_f32 v[226:227], v[46:47], v[176:177], v[226:227]
	v_pk_fma_f32 v[228:229], v[48:49], v[178:179], v[228:229]
	v_pk_fma_f32 v[230:231], v[38:39], v[182:183], v[230:231]
	v_pk_fma_f32 v[232:233], v[40:41], v[184:185], v[232:233]
	v_pk_fma_f32 v[234:235], v[26:27], v[186:187], v[234:235]
	v_pk_fma_f32 v[236:237], v[28:29], v[188:189], v[236:237]
	global_store_dwordx4 v[242:243], v[222:225], off nt
	global_store_dwordx4 v[242:243], v[226:229], off offset:64 nt
	global_store_dwordx4 v[242:243], v[230:233], off offset:512 nt
	global_store_dwordx4 v[242:243], v[234:237], off offset:576 nt
	s_waitcnt vmcnt(12)
	v_lshl_add_u64 v[162:163], v[244:245], 0, v[154:155]
	v_pk_fma_f32 v[190:191], v[34:35], v[172:173], v[190:191]
	v_pk_fma_f32 v[192:193], v[36:37], v[174:175], v[192:193]
	v_pk_fma_f32 v[194:195], v[30:31], v[176:177], v[194:195]
	v_pk_fma_f32 v[196:197], v[32:33], v[178:179], v[196:197]
	v_pk_fma_f32 v[198:199], v[22:23], v[182:183], v[198:199]
	v_pk_fma_f32 v[200:201], v[24:25], v[184:185], v[200:201]
	v_pk_fma_f32 v[202:203], v[10:11], v[186:187], v[202:203]
	v_pk_fma_f32 v[204:205], v[12:13], v[188:189], v[204:205]
	global_store_dwordx4 v[162:163], v[190:193], off nt
	global_store_dwordx4 v[162:163], v[194:197], off offset:64 nt
	global_store_dwordx4 v[162:163], v[198:201], off offset:512 nt
	global_store_dwordx4 v[162:163], v[202:205], off offset:576 nt
	s_waitcnt vmcnt(8)
	v_lshl_add_u64 v[240:241], v[244:245], 0, v[156:157]
	v_pk_fma_f32 v[206:207], v[18:19], v[172:173], v[206:207]
	v_pk_fma_f32 v[208:209], v[20:21], v[174:175], v[208:209]
	v_pk_fma_f32 v[210:211], v[14:15], v[176:177], v[210:211]
	v_pk_fma_f32 v[212:213], v[16:17], v[178:179], v[212:213]
	v_pk_fma_f32 v[214:215], v[6:7], v[182:183], v[214:215]
	v_pk_fma_f32 v[216:217], v[8:9], v[184:185], v[216:217]
	v_pk_fma_f32 v[218:219], v[2:3], v[186:187], v[218:219]
	v_pk_fma_f32 v[220:221], v[4:5], v[188:189], v[220:221]
	global_store_dwordx4 v[240:241], v[206:209], off nt
	global_store_dwordx4 v[240:241], v[210:213], off offset:64 nt
	global_store_dwordx4 v[240:241], v[214:217], off offset:512 nt
	global_store_dwordx4 v[240:241], v[218:221], off offset:576 nt
	s_and_b64 vcc, exec, s[4:5]
	s_mov_b64 s[4:5], -1
	v_readlane_b32 s54, v239, 19
	v_readlane_b32 s55, v239, 20
	v_readlane_b32 s58, v239, 23
	v_readlane_b32 s59, v239, 24
	v_readlane_b32 s60, v239, 25
	v_readlane_b32 s61, v239, 26
	v_readlane_b32 s62, v239, 27
	v_readlane_b32 s63, v239, 28
	v_readlane_b32 s64, v239, 29
	v_readlane_b32 s65, v239, 30
	v_readlane_b32 s66, v239, 31
	v_readlane_b32 s67, v239, 32
	s_cbranch_vccnz .LBB0_379
	s_andn2_b64 vcc, exec, s[12:13]
	s_cbranch_vccnz .LBB0_378
	s_barrier
	s_branch .LBB0_378

.LBB0_1104:
	s_add_i32 s2, s24, 0xffffff80
	s_ashr_i32 s17, s24, 31
	s_cmpk_lt_i32 s24, 0x80
	s_cselect_b32 s27, s17, 0
	s_cselect_b32 s26, s24, s2
	s_movk_i32 s19, 0x2400
	s_cselect_b32 s2, s87, s7
	s_cselect_b32 s17, s86, s6
	s_cselect_b32 s19, s19, 0x4800
	s_lshl_b64 s[26:27], s[26:27], 20
	s_add_u32 s26, s17, s26
	s_addc_u32 s27, s2, s27
	s_cmp_gt_i32 s24, 63
	s_cselect_b32 s2, s19, 0
	v_lshl_or_b32 v58, s25, 8, v177
	s_lshl_b32 s2, s2, 2
	s_add_u32 s24, s43, s2
	v_ashrrev_i32_e32 v59, 31, v58
	s_addc_u32 s25, s44, 0
	v_lshlrev_b64 v[174:175], 2, v[58:59]
	v_lshl_add_u64 v[58:59], s[24:25], 0, v[174:175]
	v_lshl_add_u64 v[174:175], s[26:27], 0, v[174:175]
	v_lshl_add_u64 v[186:187], v[174:175], 0, v[150:151]
	global_load_dwordx4 v[110:113], v[58:59], off
	global_load_dwordx4 v[114:117], v[58:59], off offset:64
	global_load_dwordx4 v[122:125], v[58:59], off offset:512
	global_load_dwordx4 v[182:185], v[58:59], off offset:576
	global_load_dwordx4 v[188:191], v[186:187], off nt
	global_load_dwordx4 v[192:195], v[186:187], off offset:64 nt
	global_load_dwordx4 v[196:199], v[186:187], off offset:512 nt
	global_load_dwordx4 v[200:203], v[186:187], off offset:576 nt
	v_lshl_add_u64 v[236:237], v[174:175], 0, v[160:161]
	global_load_dwordx4 v[204:207], v[236:237], off nt
	global_load_dwordx4 v[208:211], v[236:237], off offset:64 nt
	global_load_dwordx4 v[212:215], v[236:237], off offset:512 nt
	global_load_dwordx4 v[216:219], v[236:237], off offset:576 nt
	v_lshl_add_u64 v[240:241], v[174:175], 0, v[162:163]
	global_load_dwordx4 v[220:223], v[240:241], off nt
	global_load_dwordx4 v[224:227], v[240:241], off offset:64 nt
	global_load_dwordx4 v[228:231], v[240:241], off offset:512 nt
	global_load_dwordx4 v[232:235], v[240:241], off offset:576 nt
	s_waitcnt vmcnt(8)
	v_pk_fma_f32 v[188:189], v[142:143], v[110:111], v[188:189]
	v_pk_fma_f32 v[190:191], v[144:145], v[112:113], v[190:191]
	v_pk_fma_f32 v[192:193], v[138:139], v[114:115], v[192:193]
	v_pk_fma_f32 v[194:195], v[140:141], v[116:117], v[194:195]
	v_pk_fma_f32 v[196:197], v[134:135], v[122:123], v[196:197]
	v_pk_fma_f32 v[198:199], v[136:137], v[124:125], v[198:199]
	v_pk_fma_f32 v[200:201], v[126:127], v[182:183], v[200:201]
	v_pk_fma_f32 v[202:203], v[128:129], v[184:185], v[202:203]
	global_store_dwordx4 v[186:187], v[188:191], off nt
	global_store_dwordx4 v[186:187], v[192:195], off offset:64 nt
	global_store_dwordx4 v[186:187], v[196:199], off offset:512 nt
	global_store_dwordx4 v[186:187], v[200:203], off offset:576 nt
	v_lshl_add_u64 v[60:61], v[174:175], 0, v[164:165]
	global_load_dwordx4 v[188:191], v[60:61], off nt
	global_load_dwordx4 v[192:195], v[60:61], off offset:64 nt
	global_load_dwordx4 v[196:199], v[60:61], off offset:512 nt
	global_load_dwordx4 v[200:203], v[60:61], off offset:576 nt
	s_waitcnt vmcnt(12)
	v_pk_fma_f32 v[204:205], v[130:131], v[110:111], v[204:205]
	v_pk_fma_f32 v[206:207], v[132:133], v[112:113], v[206:207]
	v_pk_fma_f32 v[208:209], v[118:119], v[114:115], v[208:209]
	v_pk_fma_f32 v[210:211], v[120:121], v[116:117], v[210:211]
	v_pk_fma_f32 v[212:213], v[106:107], v[122:123], v[212:213]
	v_pk_fma_f32 v[214:215], v[108:109], v[124:125], v[214:215]
	v_pk_fma_f32 v[216:217], v[98:99], v[182:183], v[216:217]
	v_pk_fma_f32 v[218:219], v[100:101], v[184:185], v[218:219]
	global_store_dwordx4 v[236:237], v[204:207], off nt
	global_store_dwordx4 v[236:237], v[208:211], off offset:64 nt
	global_store_dwordx4 v[236:237], v[212:215], off offset:512 nt
	global_store_dwordx4 v[236:237], v[216:219], off offset:576 nt
	v_lshl_add_u64 v[236:237], v[174:175], 0, v[152:153]
	global_load_dwordx4 v[204:207], v[236:237], off nt
	global_load_dwordx4 v[208:211], v[236:237], off offset:64 nt
	global_load_dwordx4 v[212:215], v[236:237], off offset:512 nt
	global_load_dwordx4 v[216:219], v[236:237], off offset:576 nt
	s_waitcnt vmcnt(16)
	v_pk_fma_f32 v[220:221], v[102:103], v[110:111], v[220:221]
	v_pk_fma_f32 v[222:223], v[104:105], v[112:113], v[222:223]
	v_pk_fma_f32 v[224:225], v[94:95], v[114:115], v[224:225]
	v_pk_fma_f32 v[226:227], v[96:97], v[116:117], v[226:227]
	v_pk_fma_f32 v[228:229], v[90:91], v[122:123], v[228:229]
	v_pk_fma_f32 v[230:231], v[92:93], v[124:125], v[230:231]
	v_pk_fma_f32 v[232:233], v[82:83], v[182:183], v[232:233]
	v_pk_fma_f32 v[234:235], v[84:85], v[184:185], v[234:235]
	global_store_dwordx4 v[240:241], v[220:223], off nt
	global_store_dwordx4 v[240:241], v[224:227], off offset:64 nt
	global_store_dwordx4 v[240:241], v[228:231], off offset:512 nt
	global_store_dwordx4 v[240:241], v[232:235], off offset:576 nt
	v_lshl_add_u64 v[240:241], v[174:175], 0, v[154:155]
	global_load_dwordx4 v[220:223], v[240:241], off nt
	global_load_dwordx4 v[224:227], v[240:241], off offset:64 nt
	global_load_dwordx4 v[228:231], v[240:241], off offset:512 nt
	global_load_dwordx4 v[232:235], v[240:241], off offset:576 nt
	s_waitcnt vmcnt(16)
	v_pk_fma_f32 v[188:189], v[86:87], v[110:111], v[188:189]
	v_pk_fma_f32 v[190:191], v[88:89], v[112:113], v[190:191]
	v_pk_fma_f32 v[192:193], v[78:79], v[114:115], v[192:193]
	v_pk_fma_f32 v[194:195], v[80:81], v[116:117], v[194:195]
	v_pk_fma_f32 v[196:197], v[74:75], v[122:123], v[196:197]
	v_pk_fma_f32 v[198:199], v[76:77], v[124:125], v[198:199]
	v_pk_fma_f32 v[200:201], v[70:71], v[182:183], v[200:201]
	v_pk_fma_f32 v[202:203], v[72:73], v[184:185], v[202:203]
	global_store_dwordx4 v[60:61], v[188:191], off nt
	global_store_dwordx4 v[60:61], v[192:195], off offset:64 nt
	global_store_dwordx4 v[60:61], v[196:199], off offset:512 nt
	global_store_dwordx4 v[60:61], v[200:203], off offset:576 nt
	v_lshl_add_u64 v[60:61], v[174:175], 0, v[156:157]
	global_load_dwordx4 v[188:191], v[60:61], off nt
	global_load_dwordx4 v[192:195], v[60:61], off offset:64 nt
	global_load_dwordx4 v[196:199], v[60:61], off offset:512 nt
	global_load_dwordx4 v[200:203], v[60:61], off offset:576 nt
	s_waitcnt vmcnt(16)
	v_pk_fma_f32 v[204:205], v[66:67], v[110:111], v[204:205]
	v_pk_fma_f32 v[206:207], v[68:69], v[112:113], v[206:207]
	v_pk_fma_f32 v[208:209], v[62:63], v[114:115], v[208:209]
	v_pk_fma_f32 v[210:211], v[64:65], v[116:117], v[210:211]
	v_pk_fma_f32 v[212:213], v[54:55], v[122:123], v[212:213]
	v_pk_fma_f32 v[214:215], v[56:57], v[124:125], v[214:215]
	v_pk_fma_f32 v[216:217], v[50:51], v[182:183], v[216:217]
	v_pk_fma_f32 v[218:219], v[52:53], v[184:185], v[218:219]
	global_store_dwordx4 v[236:237], v[204:207], off nt
	global_store_dwordx4 v[236:237], v[208:211], off offset:64 nt
	global_store_dwordx4 v[236:237], v[212:215], off offset:512 nt
	global_store_dwordx4 v[236:237], v[216:219], off offset:576 nt
	v_lshl_add_u64 v[236:237], v[174:175], 0, v[158:159]
	global_load_dwordx4 v[204:207], v[236:237], off nt
	global_load_dwordx4 v[208:211], v[236:237], off offset:64 nt
	global_load_dwordx4 v[212:215], v[236:237], off offset:512 nt
	global_load_dwordx4 v[216:219], v[236:237], off offset:576 nt
	s_waitcnt vmcnt(16)
	v_pk_fma_f32 v[220:221], v[46:47], v[110:111], v[220:221]
	v_pk_fma_f32 v[222:223], v[48:49], v[112:113], v[222:223]
	v_pk_fma_f32 v[224:225], v[42:43], v[114:115], v[224:225]
	v_pk_fma_f32 v[226:227], v[44:45], v[116:117], v[226:227]
	v_pk_fma_f32 v[228:229], v[38:39], v[122:123], v[228:229]
	v_pk_fma_f32 v[230:231], v[40:41], v[124:125], v[230:231]
	v_pk_fma_f32 v[232:233], v[34:35], v[182:183], v[232:233]
	v_pk_fma_f32 v[234:235], v[36:37], v[184:185], v[234:235]
	global_store_dwordx4 v[240:241], v[220:223], off nt
	global_store_dwordx4 v[240:241], v[224:227], off offset:64 nt
	global_store_dwordx4 v[240:241], v[228:231], off offset:512 nt
	global_store_dwordx4 v[240:241], v[232:235], off offset:576 nt
	s_waitcnt vmcnt(12)
	v_pk_fma_f32 v[188:189], v[30:31], v[110:111], v[188:189]
	v_pk_fma_f32 v[190:191], v[32:33], v[112:113], v[190:191]
	v_pk_fma_f32 v[192:193], v[26:27], v[114:115], v[192:193]
	v_pk_fma_f32 v[194:195], v[28:29], v[116:117], v[194:195]
	v_pk_fma_f32 v[196:197], v[22:23], v[122:123], v[196:197]
	v_pk_fma_f32 v[198:199], v[24:25], v[124:125], v[198:199]
	v_pk_fma_f32 v[200:201], v[18:19], v[182:183], v[200:201]
	v_pk_fma_f32 v[202:203], v[20:21], v[184:185], v[202:203]
	global_store_dwordx4 v[60:61], v[188:191], off nt
	global_store_dwordx4 v[60:61], v[192:195], off offset:64 nt
	global_store_dwordx4 v[60:61], v[196:199], off offset:512 nt
	global_store_dwordx4 v[60:61], v[200:203], off offset:576 nt
	s_waitcnt vmcnt(8)
	v_pk_fma_f32 v[204:205], v[14:15], v[110:111], v[204:205]
	v_pk_fma_f32 v[206:207], v[16:17], v[112:113], v[206:207]
	v_pk_fma_f32 v[208:209], v[10:11], v[114:115], v[208:209]
	v_pk_fma_f32 v[210:211], v[12:13], v[116:117], v[210:211]
	v_pk_fma_f32 v[212:213], v[6:7], v[122:123], v[212:213]
	v_pk_fma_f32 v[214:215], v[8:9], v[124:125], v[214:215]
	v_pk_fma_f32 v[216:217], v[2:3], v[182:183], v[216:217]
	v_pk_fma_f32 v[218:219], v[4:5], v[184:185], v[218:219]
	global_store_dwordx4 v[236:237], v[204:207], off nt
	global_store_dwordx4 v[236:237], v[208:211], off offset:64 nt
	global_store_dwordx4 v[236:237], v[212:215], off offset:512 nt
	global_store_dwordx4 v[236:237], v[216:219], off offset:576 nt
	s_mov_b64 s[24:25], -1
	s_andn2_b64 vcc, exec, s[4:5]
	s_cbranch_vccnz .LBB0_1093
	s_andn2_b64 vcc, exec, s[10:11]
	s_cbranch_vccnz .LBB0_1092
	s_barrier
	s_branch .LBB0_1092

.LBB0_1370:
	s_add_i32 s2, s47, 0xffffff80
	s_ashr_i32 s20, s47, 31
	s_cmpk_lt_i32 s47, 0x80
	s_cselect_b32 s21, s20, 0
	s_cselect_b32 s20, s47, s2
	s_movk_i32 s23, 0x2400
	s_cselect_b32 s2, s87, s9
	s_cselect_b32 s22, s86, s8
	s_cselect_b32 s23, s23, 0x4800
	s_lshl_b64 s[20:21], s[20:21], 20
	s_add_u32 s20, s22, s20
	s_addc_u32 s21, s2, s21
	s_cmp_gt_i32 s47, 63
	s_cselect_b32 s2, s23, 0
	v_lshl_or_b32 v158, s48, 8, v177
	s_lshl_b32 s2, s2, 2
	s_add_u32 s22, s37, s2
	v_ashrrev_i32_e32 v159, 31, v158
	s_addc_u32 s23, s38, 0
	v_lshlrev_b64 v[174:175], 2, v[158:159]
	v_lshl_add_u64 v[182:183], s[22:23], 0, v[174:175]
	global_load_dwordx4 v[158:161], v[182:183], off
	global_load_dwordx4 v[162:165], v[182:183], off offset:64
	global_load_dwordx4 v[166:169], v[182:183], off offset:512
	global_load_dwordx4 v[170:173], v[182:183], off offset:576
	v_lshl_add_u64 v[240:241], s[20:21], 0, v[174:175]
	v_lshl_add_u64 v[232:233], v[240:241], 0, v[134:135]
	global_load_dwordx4 v[184:187], v[232:233], off nt
	global_load_dwordx4 v[188:191], v[232:233], off offset:64 nt
	global_load_dwordx4 v[192:195], v[232:233], off offset:512 nt
	global_load_dwordx4 v[196:199], v[232:233], off offset:576 nt
	v_lshl_add_u64 v[234:235], v[240:241], 0, v[144:145]
	global_load_dwordx4 v[200:203], v[234:235], off nt
	global_load_dwordx4 v[204:207], v[234:235], off offset:64 nt
	global_load_dwordx4 v[208:211], v[234:235], off offset:512 nt
	global_load_dwordx4 v[212:215], v[234:235], off offset:576 nt
	v_lshl_add_u64 v[236:237], v[240:241], 0, v[146:147]
	global_load_dwordx4 v[216:219], v[236:237], off nt
	global_load_dwordx4 v[220:223], v[236:237], off offset:64 nt
	global_load_dwordx4 v[224:227], v[236:237], off offset:512 nt
	global_load_dwordx4 v[228:231], v[236:237], off offset:576 nt
	s_waitcnt vmcnt(8)
	v_pk_mul_f32 v[158:159], v[158:159], 0.5 op_sel_hi:[1,0]
	v_pk_mul_f32 v[160:161], v[160:161], 0.5 op_sel_hi:[1,0]
	v_pk_mul_f32 v[162:163], v[162:163], 0.5 op_sel_hi:[1,0]
	v_pk_mul_f32 v[164:165], v[164:165], 0.5 op_sel_hi:[1,0]
	v_pk_mul_f32 v[166:167], v[166:167], 0.5 op_sel_hi:[1,0]
	v_pk_mul_f32 v[168:169], v[168:169], 0.5 op_sel_hi:[1,0]
	v_pk_mul_f32 v[170:171], v[170:171], 0.5 op_sel_hi:[1,0]
	v_pk_mul_f32 v[172:173], v[172:173], 0.5 op_sel_hi:[1,0]
	v_pk_fma_f32 v[184:185], v[126:127], v[158:159], v[184:185]
	v_pk_fma_f32 v[186:187], v[128:129], v[160:161], v[186:187]
	v_pk_fma_f32 v[188:189], v[122:123], v[162:163], v[188:189]
	v_pk_fma_f32 v[190:191], v[124:125], v[164:165], v[190:191]
	v_pk_fma_f32 v[192:193], v[118:119], v[166:167], v[192:193]
	v_pk_fma_f32 v[194:195], v[120:121], v[168:169], v[194:195]
	v_pk_fma_f32 v[196:197], v[110:111], v[170:171], v[196:197]
	v_pk_fma_f32 v[198:199], v[112:113], v[172:173], v[198:199]
	global_store_dwordx4 v[232:233], v[184:187], off nt
	global_store_dwordx4 v[232:233], v[188:191], off offset:64 nt
	global_store_dwordx4 v[232:233], v[192:195], off offset:512 nt
	global_store_dwordx4 v[232:233], v[196:199], off offset:576 nt
	v_lshl_add_u64 v[232:233], v[240:241], 0, v[148:149]
	global_load_dwordx4 v[184:187], v[232:233], off nt
	global_load_dwordx4 v[188:191], v[232:233], off offset:64 nt
	global_load_dwordx4 v[192:195], v[232:233], off offset:512 nt
	global_load_dwordx4 v[196:199], v[232:233], off offset:576 nt
	s_waitcnt vmcnt(12)
	v_pk_fma_f32 v[200:201], v[114:115], v[158:159], v[200:201]
	v_pk_fma_f32 v[202:203], v[116:117], v[160:161], v[202:203]
	v_pk_fma_f32 v[204:205], v[106:107], v[162:163], v[204:205]
	v_pk_fma_f32 v[206:207], v[108:109], v[164:165], v[206:207]
	v_pk_fma_f32 v[208:209], v[102:103], v[166:167], v[208:209]
	v_pk_fma_f32 v[210:211], v[104:105], v[168:169], v[210:211]
	v_pk_fma_f32 v[212:213], v[94:95], v[170:171], v[212:213]
	v_pk_fma_f32 v[214:215], v[96:97], v[172:173], v[214:215]
	global_store_dwordx4 v[234:235], v[200:203], off nt
	global_store_dwordx4 v[234:235], v[204:207], off offset:64 nt
	global_store_dwordx4 v[234:235], v[208:211], off offset:512 nt
	global_store_dwordx4 v[234:235], v[212:215], off offset:576 nt
	v_lshl_add_u64 v[234:235], v[240:241], 0, v[136:137]
	global_load_dwordx4 v[200:203], v[234:235], off nt
	global_load_dwordx4 v[204:207], v[234:235], off offset:64 nt
	global_load_dwordx4 v[208:211], v[234:235], off offset:512 nt
	global_load_dwordx4 v[212:215], v[234:235], off offset:576 nt
	s_waitcnt vmcnt(16)
	v_pk_fma_f32 v[216:217], v[98:99], v[158:159], v[216:217]
	v_pk_fma_f32 v[218:219], v[100:101], v[160:161], v[218:219]
	v_pk_fma_f32 v[220:221], v[90:91], v[162:163], v[220:221]
	v_pk_fma_f32 v[222:223], v[92:93], v[164:165], v[222:223]
	v_pk_fma_f32 v[224:225], v[86:87], v[166:167], v[224:225]
	v_pk_fma_f32 v[226:227], v[88:89], v[168:169], v[226:227]
	v_pk_fma_f32 v[228:229], v[82:83], v[170:171], v[228:229]
	v_pk_fma_f32 v[230:231], v[84:85], v[172:173], v[230:231]
	global_store_dwordx4 v[236:237], v[216:219], off nt
	global_store_dwordx4 v[236:237], v[220:223], off offset:64 nt
	global_store_dwordx4 v[236:237], v[224:227], off offset:512 nt
	global_store_dwordx4 v[236:237], v[228:231], off offset:576 nt
	v_lshl_add_u64 v[236:237], v[240:241], 0, v[138:139]
	global_load_dwordx4 v[216:219], v[236:237], off nt
	global_load_dwordx4 v[220:223], v[236:237], off offset:64 nt
	global_load_dwordx4 v[224:227], v[236:237], off offset:512 nt
	global_load_dwordx4 v[228:231], v[236:237], off offset:576 nt
	s_waitcnt vmcnt(16)
	v_pk_fma_f32 v[184:185], v[78:79], v[158:159], v[184:185]
	v_pk_fma_f32 v[186:187], v[80:81], v[160:161], v[186:187]
	v_pk_fma_f32 v[188:189], v[74:75], v[162:163], v[188:189]
	v_pk_fma_f32 v[190:191], v[76:77], v[164:165], v[190:191]
	v_pk_fma_f32 v[192:193], v[70:71], v[166:167], v[192:193]
	v_pk_fma_f32 v[194:195], v[72:73], v[168:169], v[194:195]
	v_pk_fma_f32 v[196:197], v[66:67], v[170:171], v[196:197]
	v_pk_fma_f32 v[198:199], v[68:69], v[172:173], v[198:199]
	global_store_dwordx4 v[232:233], v[184:187], off nt
	global_store_dwordx4 v[232:233], v[188:191], off offset:64 nt
	global_store_dwordx4 v[232:233], v[192:195], off offset:512 nt
	global_store_dwordx4 v[232:233], v[196:199], off offset:576 nt
	v_lshl_add_u64 v[232:233], v[240:241], 0, v[140:141]
	global_load_dwordx4 v[184:187], v[232:233], off nt
	global_load_dwordx4 v[188:191], v[232:233], off offset:64 nt
	global_load_dwordx4 v[192:195], v[232:233], off offset:512 nt
	global_load_dwordx4 v[196:199], v[232:233], off offset:576 nt
	s_waitcnt vmcnt(16)
	v_pk_fma_f32 v[200:201], v[62:63], v[158:159], v[200:201]
	v_pk_fma_f32 v[202:203], v[64:65], v[160:161], v[202:203]
	v_pk_fma_f32 v[204:205], v[58:59], v[162:163], v[204:205]
	v_pk_fma_f32 v[206:207], v[60:61], v[164:165], v[206:207]
	v_pk_fma_f32 v[208:209], v[54:55], v[166:167], v[208:209]
	v_pk_fma_f32 v[210:211], v[56:57], v[168:169], v[210:211]
	v_pk_fma_f32 v[212:213], v[50:51], v[170:171], v[212:213]
	v_pk_fma_f32 v[214:215], v[52:53], v[172:173], v[214:215]
	global_store_dwordx4 v[234:235], v[200:203], off nt
	global_store_dwordx4 v[234:235], v[204:207], off offset:64 nt
	global_store_dwordx4 v[234:235], v[208:211], off offset:512 nt
	global_store_dwordx4 v[234:235], v[212:215], off offset:576 nt
	v_lshl_add_u64 v[234:235], v[240:241], 0, v[142:143]
	global_load_dwordx4 v[200:203], v[234:235], off nt
	global_load_dwordx4 v[204:207], v[234:235], off offset:64 nt
	global_load_dwordx4 v[208:211], v[234:235], off offset:512 nt
	global_load_dwordx4 v[212:215], v[234:235], off offset:576 nt
	s_waitcnt vmcnt(16)
	v_pk_fma_f32 v[216:217], v[46:47], v[158:159], v[216:217]
	v_pk_fma_f32 v[218:219], v[48:49], v[160:161], v[218:219]
	v_pk_fma_f32 v[220:221], v[42:43], v[162:163], v[220:221]
	v_pk_fma_f32 v[222:223], v[44:45], v[164:165], v[222:223]
	v_pk_fma_f32 v[224:225], v[38:39], v[166:167], v[224:225]
	v_pk_fma_f32 v[226:227], v[40:41], v[168:169], v[226:227]
	v_pk_fma_f32 v[228:229], v[34:35], v[170:171], v[228:229]
	v_pk_fma_f32 v[230:231], v[36:37], v[172:173], v[230:231]
	global_store_dwordx4 v[236:237], v[216:219], off nt
	global_store_dwordx4 v[236:237], v[220:223], off offset:64 nt
	global_store_dwordx4 v[236:237], v[224:227], off offset:512 nt
	global_store_dwordx4 v[236:237], v[228:231], off offset:576 nt
	s_waitcnt vmcnt(12)
	v_pk_fma_f32 v[184:185], v[30:31], v[158:159], v[184:185]
	v_pk_fma_f32 v[186:187], v[32:33], v[160:161], v[186:187]
	v_pk_fma_f32 v[188:189], v[26:27], v[162:163], v[188:189]
	v_pk_fma_f32 v[190:191], v[28:29], v[164:165], v[190:191]
	v_pk_fma_f32 v[192:193], v[22:23], v[166:167], v[192:193]
	v_pk_fma_f32 v[194:195], v[24:25], v[168:169], v[194:195]
	v_pk_fma_f32 v[196:197], v[18:19], v[170:171], v[196:197]
	v_pk_fma_f32 v[198:199], v[20:21], v[172:173], v[198:199]
	global_store_dwordx4 v[232:233], v[184:187], off nt
	global_store_dwordx4 v[232:233], v[188:191], off offset:64 nt
	global_store_dwordx4 v[232:233], v[192:195], off offset:512 nt
	global_store_dwordx4 v[232:233], v[196:199], off offset:576 nt
	s_waitcnt vmcnt(8)
	v_pk_fma_f32 v[200:201], v[14:15], v[158:159], v[200:201]
	v_pk_fma_f32 v[202:203], v[16:17], v[160:161], v[202:203]
	v_pk_fma_f32 v[204:205], v[10:11], v[162:163], v[204:205]
	v_pk_fma_f32 v[206:207], v[12:13], v[164:165], v[206:207]
	v_pk_fma_f32 v[208:209], v[6:7], v[166:167], v[208:209]
	v_pk_fma_f32 v[210:211], v[8:9], v[168:169], v[210:211]
	v_pk_fma_f32 v[212:213], v[2:3], v[170:171], v[212:213]
	v_pk_fma_f32 v[214:215], v[4:5], v[172:173], v[214:215]
	global_store_dwordx4 v[234:235], v[200:203], off nt
	global_store_dwordx4 v[234:235], v[204:207], off offset:64 nt
	global_store_dwordx4 v[234:235], v[208:211], off offset:512 nt
	global_store_dwordx4 v[234:235], v[212:215], off offset:576 nt
	s_mov_b64 s[20:21], -1
	s_and_b64 vcc, exec, s[4:5]
	s_cbranch_vccnz .LBB0_1355
	s_andn2_b64 vcc, exec, s[12:13]
	s_cbranch_vccnz .LBB0_1354
	s_barrier
	s_branch .LBB0_1354

.LBB0_2331:
	s_add_i32 s2, s20, 0xffffff80
	s_ashr_i32 s13, s20, 31
	s_cmpk_lt_i32 s20, 0x80
	s_cselect_b32 s23, s13, 0
	s_cselect_b32 s22, s20, s2
	s_cselect_b32 s2, s87, s42
	s_cselect_b32 s13, s86, s41
	s_cselect_b32 s15, s51, 0x4800
	s_lshl_b64 s[22:23], s[22:23], 20
	s_add_u32 s22, s13, s22
	s_addc_u32 s23, s2, s23
	s_cmp_gt_i32 s20, 63
	s_cselect_b32 s2, s15, 0
	v_lshl_or_b32 v86, s21, 8, v177
	s_lshl_b32 s2, s2, 2
	s_add_u32 s20, s43, s2
	v_ashrrev_i32_e32 v87, 31, v86
	s_addc_u32 s21, s44, 0
	v_lshlrev_b64 v[174:175], 2, v[86:87]
	v_lshl_add_u64 v[86:87], s[20:21], 0, v[174:175]
	v_lshl_add_u64 v[174:175], s[22:23], 0, v[174:175]
	v_lshl_add_u64 v[186:187], v[174:175], 0, v[150:151]
	global_load_dwordx4 v[126:129], v[86:87], off
	global_load_dwordx4 v[130:133], v[86:87], off offset:64
	global_load_dwordx4 v[138:141], v[86:87], off offset:512
	global_load_dwordx4 v[182:185], v[86:87], off offset:576
	global_load_dwordx4 v[188:191], v[186:187], off nt
	global_load_dwordx4 v[192:195], v[186:187], off offset:64 nt
	global_load_dwordx4 v[196:199], v[186:187], off offset:512 nt
	global_load_dwordx4 v[200:203], v[186:187], off offset:576 nt
	v_lshl_add_u64 v[236:237], v[174:175], 0, v[160:161]
	global_load_dwordx4 v[204:207], v[236:237], off nt
	global_load_dwordx4 v[208:211], v[236:237], off offset:64 nt
	global_load_dwordx4 v[212:215], v[236:237], off offset:512 nt
	global_load_dwordx4 v[216:219], v[236:237], off offset:576 nt
	v_lshl_add_u64 v[240:241], v[174:175], 0, v[162:163]
	global_load_dwordx4 v[220:223], v[240:241], off nt
	global_load_dwordx4 v[224:227], v[240:241], off offset:64 nt
	global_load_dwordx4 v[228:231], v[240:241], off offset:512 nt
	global_load_dwordx4 v[232:235], v[240:241], off offset:576 nt
	s_waitcnt vmcnt(8)
	v_pk_fma_f32 v[188:189], v[142:143], v[126:127], v[188:189]
	v_pk_fma_f32 v[190:191], v[144:145], v[128:129], v[190:191]
	v_pk_fma_f32 v[192:193], v[134:135], v[130:131], v[192:193]
	v_pk_fma_f32 v[194:195], v[136:137], v[132:133], v[194:195]
	v_pk_fma_f32 v[196:197], v[122:123], v[138:139], v[196:197]
	v_pk_fma_f32 v[198:199], v[124:125], v[140:141], v[198:199]
	v_pk_fma_f32 v[200:201], v[114:115], v[182:183], v[200:201]
	v_pk_fma_f32 v[202:203], v[116:117], v[184:185], v[202:203]
	global_store_dwordx4 v[186:187], v[188:191], off nt
	global_store_dwordx4 v[186:187], v[192:195], off offset:64 nt
	global_store_dwordx4 v[186:187], v[196:199], off offset:512 nt
	global_store_dwordx4 v[186:187], v[200:203], off offset:576 nt
	v_lshl_add_u64 v[88:89], v[174:175], 0, v[164:165]
	global_load_dwordx4 v[188:191], v[88:89], off nt
	global_load_dwordx4 v[192:195], v[88:89], off offset:64 nt
	global_load_dwordx4 v[196:199], v[88:89], off offset:512 nt
	global_load_dwordx4 v[200:203], v[88:89], off offset:576 nt
	s_waitcnt vmcnt(12)
	v_pk_fma_f32 v[204:205], v[118:119], v[126:127], v[204:205]
	v_pk_fma_f32 v[206:207], v[120:121], v[128:129], v[206:207]
	v_pk_fma_f32 v[208:209], v[110:111], v[130:131], v[208:209]
	v_pk_fma_f32 v[210:211], v[112:113], v[132:133], v[210:211]
	v_pk_fma_f32 v[212:213], v[106:107], v[138:139], v[212:213]
	v_pk_fma_f32 v[214:215], v[108:109], v[140:141], v[214:215]
	v_pk_fma_f32 v[216:217], v[98:99], v[182:183], v[216:217]
	v_pk_fma_f32 v[218:219], v[100:101], v[184:185], v[218:219]
	global_store_dwordx4 v[236:237], v[204:207], off nt
	global_store_dwordx4 v[236:237], v[208:211], off offset:64 nt
	global_store_dwordx4 v[236:237], v[212:215], off offset:512 nt
	global_store_dwordx4 v[236:237], v[216:219], off offset:576 nt
	v_lshl_add_u64 v[236:237], v[174:175], 0, v[152:153]
	global_load_dwordx4 v[204:207], v[236:237], off nt
	global_load_dwordx4 v[208:211], v[236:237], off offset:64 nt
	global_load_dwordx4 v[212:215], v[236:237], off offset:512 nt
	global_load_dwordx4 v[216:219], v[236:237], off offset:576 nt
	s_waitcnt vmcnt(16)
	v_pk_fma_f32 v[220:221], v[102:103], v[126:127], v[220:221]
	v_pk_fma_f32 v[222:223], v[104:105], v[128:129], v[222:223]
	v_pk_fma_f32 v[224:225], v[94:95], v[130:131], v[224:225]
	v_pk_fma_f32 v[226:227], v[96:97], v[132:133], v[226:227]
	v_pk_fma_f32 v[228:229], v[90:91], v[138:139], v[228:229]
	v_pk_fma_f32 v[230:231], v[92:93], v[140:141], v[230:231]
	v_pk_fma_f32 v[232:233], v[78:79], v[182:183], v[232:233]
	v_pk_fma_f32 v[234:235], v[80:81], v[184:185], v[234:235]
	global_store_dwordx4 v[240:241], v[220:223], off nt
	global_store_dwordx4 v[240:241], v[224:227], off offset:64 nt
	global_store_dwordx4 v[240:241], v[228:231], off offset:512 nt
	global_store_dwordx4 v[240:241], v[232:235], off offset:576 nt
	v_lshl_add_u64 v[240:241], v[174:175], 0, v[154:155]
	global_load_dwordx4 v[220:223], v[240:241], off nt
	global_load_dwordx4 v[224:227], v[240:241], off offset:64 nt
	global_load_dwordx4 v[228:231], v[240:241], off offset:512 nt
	global_load_dwordx4 v[232:235], v[240:241], off offset:576 nt
	s_waitcnt vmcnt(16)
	v_pk_fma_f32 v[188:189], v[82:83], v[126:127], v[188:189]
	v_pk_fma_f32 v[190:191], v[84:85], v[128:129], v[190:191]
	v_pk_fma_f32 v[192:193], v[74:75], v[130:131], v[192:193]
	v_pk_fma_f32 v[194:195], v[76:77], v[132:133], v[194:195]
	v_pk_fma_f32 v[196:197], v[70:71], v[138:139], v[196:197]
	v_pk_fma_f32 v[198:199], v[72:73], v[140:141], v[198:199]
	v_pk_fma_f32 v[200:201], v[66:67], v[182:183], v[200:201]
	v_pk_fma_f32 v[202:203], v[68:69], v[184:185], v[202:203]
	global_store_dwordx4 v[88:89], v[188:191], off nt
	global_store_dwordx4 v[88:89], v[192:195], off offset:64 nt
	global_store_dwordx4 v[88:89], v[196:199], off offset:512 nt
	global_store_dwordx4 v[88:89], v[200:203], off offset:576 nt
	v_lshl_add_u64 v[88:89], v[174:175], 0, v[156:157]
	global_load_dwordx4 v[188:191], v[88:89], off nt
	global_load_dwordx4 v[192:195], v[88:89], off offset:64 nt
	global_load_dwordx4 v[196:199], v[88:89], off offset:512 nt
	global_load_dwordx4 v[200:203], v[88:89], off offset:576 nt
	s_waitcnt vmcnt(16)
	v_pk_fma_f32 v[204:205], v[62:63], v[126:127], v[204:205]
	v_pk_fma_f32 v[206:207], v[64:65], v[128:129], v[206:207]
	v_pk_fma_f32 v[208:209], v[58:59], v[130:131], v[208:209]
	v_pk_fma_f32 v[210:211], v[60:61], v[132:133], v[210:211]
	v_pk_fma_f32 v[212:213], v[54:55], v[138:139], v[212:213]
	v_pk_fma_f32 v[214:215], v[56:57], v[140:141], v[214:215]
	v_pk_fma_f32 v[216:217], v[50:51], v[182:183], v[216:217]
	v_pk_fma_f32 v[218:219], v[52:53], v[184:185], v[218:219]
	global_store_dwordx4 v[236:237], v[204:207], off nt
	global_store_dwordx4 v[236:237], v[208:211], off offset:64 nt
	global_store_dwordx4 v[236:237], v[212:215], off offset:512 nt
	global_store_dwordx4 v[236:237], v[216:219], off offset:576 nt
	v_lshl_add_u64 v[236:237], v[174:175], 0, v[158:159]
	global_load_dwordx4 v[204:207], v[236:237], off nt
	global_load_dwordx4 v[208:211], v[236:237], off offset:64 nt
	global_load_dwordx4 v[212:215], v[236:237], off offset:512 nt
	global_load_dwordx4 v[216:219], v[236:237], off offset:576 nt
	s_waitcnt vmcnt(16)
	v_pk_fma_f32 v[220:221], v[46:47], v[126:127], v[220:221]
	v_pk_fma_f32 v[222:223], v[48:49], v[128:129], v[222:223]
	v_pk_fma_f32 v[224:225], v[42:43], v[130:131], v[224:225]
	v_pk_fma_f32 v[226:227], v[44:45], v[132:133], v[226:227]
	v_pk_fma_f32 v[228:229], v[38:39], v[138:139], v[228:229]
	v_pk_fma_f32 v[230:231], v[40:41], v[140:141], v[230:231]
	v_pk_fma_f32 v[232:233], v[34:35], v[182:183], v[232:233]
	v_pk_fma_f32 v[234:235], v[36:37], v[184:185], v[234:235]
	global_store_dwordx4 v[240:241], v[220:223], off nt
	global_store_dwordx4 v[240:241], v[224:227], off offset:64 nt
	global_store_dwordx4 v[240:241], v[228:231], off offset:512 nt
	global_store_dwordx4 v[240:241], v[232:235], off offset:576 nt
	s_waitcnt vmcnt(12)
	v_pk_fma_f32 v[188:189], v[30:31], v[126:127], v[188:189]
	v_pk_fma_f32 v[190:191], v[32:33], v[128:129], v[190:191]
	v_pk_fma_f32 v[192:193], v[26:27], v[130:131], v[192:193]
	v_pk_fma_f32 v[194:195], v[28:29], v[132:133], v[194:195]
	v_pk_fma_f32 v[196:197], v[22:23], v[138:139], v[196:197]
	v_pk_fma_f32 v[198:199], v[24:25], v[140:141], v[198:199]
	v_pk_fma_f32 v[200:201], v[14:15], v[182:183], v[200:201]
	v_pk_fma_f32 v[202:203], v[16:17], v[184:185], v[202:203]
	global_store_dwordx4 v[88:89], v[188:191], off nt
	global_store_dwordx4 v[88:89], v[192:195], off offset:64 nt
	global_store_dwordx4 v[88:89], v[196:199], off offset:512 nt
	global_store_dwordx4 v[88:89], v[200:203], off offset:576 nt
	s_waitcnt vmcnt(8)
	v_pk_fma_f32 v[204:205], v[18:19], v[126:127], v[204:205]
	v_pk_fma_f32 v[206:207], v[20:21], v[128:129], v[206:207]
	v_pk_fma_f32 v[208:209], v[10:11], v[130:131], v[208:209]
	v_pk_fma_f32 v[210:211], v[12:13], v[132:133], v[210:211]
	v_pk_fma_f32 v[212:213], v[6:7], v[138:139], v[212:213]
	v_pk_fma_f32 v[214:215], v[8:9], v[140:141], v[214:215]
	v_pk_fma_f32 v[216:217], v[2:3], v[182:183], v[216:217]
	v_pk_fma_f32 v[218:219], v[4:5], v[184:185], v[218:219]
	global_store_dwordx4 v[236:237], v[204:207], off nt
	global_store_dwordx4 v[236:237], v[208:211], off offset:64 nt
	global_store_dwordx4 v[236:237], v[212:215], off offset:512 nt
	global_store_dwordx4 v[236:237], v[216:219], off offset:576 nt
	s_mov_b64 s[20:21], -1
	s_andn2_b64 vcc, exec, s[4:5]
	s_cbranch_vccnz .LBB0_2320
	s_andn2_b64 vcc, exec, s[6:7]
	s_cbranch_vccnz .LBB0_2319
	s_barrier
	s_branch .LBB0_2319

.LBB0_2586:
	s_add_i32 s2, s48, 0xffffff80
	s_ashr_i32 s16, s48, 31
	s_cmpk_lt_i32 s48, 0x80
	s_cselect_b32 s17, s16, 0
	s_cselect_b32 s16, s48, s2
	s_cselect_b32 s2, s87, s36
	s_cselect_b32 s18, s86, s35
	s_cselect_b32 s19, s45, 0x4800
	s_lshl_b64 s[16:17], s[16:17], 20
	s_add_u32 s16, s18, s16
	s_addc_u32 s17, s2, s17
	s_cmp_gt_i32 s48, 63
	s_cselect_b32 s2, s19, 0
	v_lshl_or_b32 v158, s49, 8, v177
	s_lshl_b32 s2, s2, 2
	s_add_u32 s18, s37, s2
	v_ashrrev_i32_e32 v159, 31, v158
	s_addc_u32 s19, s38, 0
	v_lshlrev_b64 v[174:175], 2, v[158:159]
	v_lshl_add_u64 v[182:183], s[18:19], 0, v[174:175]
	global_load_dwordx4 v[158:161], v[182:183], off
	global_load_dwordx4 v[162:165], v[182:183], off offset:64
	global_load_dwordx4 v[166:169], v[182:183], off offset:512
	global_load_dwordx4 v[170:173], v[182:183], off offset:576
	v_lshl_add_u64 v[240:241], s[16:17], 0, v[174:175]
	v_lshl_add_u64 v[232:233], v[240:241], 0, v[134:135]
	global_load_dwordx4 v[184:187], v[232:233], off nt
	global_load_dwordx4 v[188:191], v[232:233], off offset:64 nt
	global_load_dwordx4 v[192:195], v[232:233], off offset:512 nt
	global_load_dwordx4 v[196:199], v[232:233], off offset:576 nt
	v_lshl_add_u64 v[234:235], v[240:241], 0, v[144:145]
	global_load_dwordx4 v[200:203], v[234:235], off nt
	global_load_dwordx4 v[204:207], v[234:235], off offset:64 nt
	global_load_dwordx4 v[208:211], v[234:235], off offset:512 nt
	global_load_dwordx4 v[212:215], v[234:235], off offset:576 nt
	v_lshl_add_u64 v[236:237], v[240:241], 0, v[146:147]
	global_load_dwordx4 v[216:219], v[236:237], off nt
	global_load_dwordx4 v[220:223], v[236:237], off offset:64 nt
	global_load_dwordx4 v[224:227], v[236:237], off offset:512 nt
	global_load_dwordx4 v[228:231], v[236:237], off offset:576 nt
	s_waitcnt vmcnt(8)
	v_pk_mul_f32 v[158:159], v[158:159], 0.5 op_sel_hi:[1,0]
	v_pk_mul_f32 v[160:161], v[160:161], 0.5 op_sel_hi:[1,0]
	v_pk_mul_f32 v[162:163], v[162:163], 0.5 op_sel_hi:[1,0]
	v_pk_mul_f32 v[164:165], v[164:165], 0.5 op_sel_hi:[1,0]
	v_pk_mul_f32 v[166:167], v[166:167], 0.5 op_sel_hi:[1,0]
	v_pk_mul_f32 v[168:169], v[168:169], 0.5 op_sel_hi:[1,0]
	v_pk_mul_f32 v[170:171], v[170:171], 0.5 op_sel_hi:[1,0]
	v_pk_mul_f32 v[172:173], v[172:173], 0.5 op_sel_hi:[1,0]
	v_pk_fma_f32 v[184:185], v[126:127], v[158:159], v[184:185]
	v_pk_fma_f32 v[186:187], v[128:129], v[160:161], v[186:187]
	v_pk_fma_f32 v[188:189], v[122:123], v[162:163], v[188:189]
	v_pk_fma_f32 v[190:191], v[124:125], v[164:165], v[190:191]
	v_pk_fma_f32 v[192:193], v[118:119], v[166:167], v[192:193]
	v_pk_fma_f32 v[194:195], v[120:121], v[168:169], v[194:195]
	v_pk_fma_f32 v[196:197], v[110:111], v[170:171], v[196:197]
	v_pk_fma_f32 v[198:199], v[112:113], v[172:173], v[198:199]
	global_store_dwordx4 v[232:233], v[184:187], off nt
	global_store_dwordx4 v[232:233], v[188:191], off offset:64 nt
	global_store_dwordx4 v[232:233], v[192:195], off offset:512 nt
	global_store_dwordx4 v[232:233], v[196:199], off offset:576 nt
	v_lshl_add_u64 v[232:233], v[240:241], 0, v[148:149]
	global_load_dwordx4 v[184:187], v[232:233], off nt
	global_load_dwordx4 v[188:191], v[232:233], off offset:64 nt
	global_load_dwordx4 v[192:195], v[232:233], off offset:512 nt
	global_load_dwordx4 v[196:199], v[232:233], off offset:576 nt
	s_waitcnt vmcnt(12)
	v_pk_fma_f32 v[200:201], v[114:115], v[158:159], v[200:201]
	v_pk_fma_f32 v[202:203], v[116:117], v[160:161], v[202:203]
	v_pk_fma_f32 v[204:205], v[106:107], v[162:163], v[204:205]
	v_pk_fma_f32 v[206:207], v[108:109], v[164:165], v[206:207]
	v_pk_fma_f32 v[208:209], v[102:103], v[166:167], v[208:209]
	v_pk_fma_f32 v[210:211], v[104:105], v[168:169], v[210:211]
	v_pk_fma_f32 v[212:213], v[94:95], v[170:171], v[212:213]
	v_pk_fma_f32 v[214:215], v[96:97], v[172:173], v[214:215]
	global_store_dwordx4 v[234:235], v[200:203], off nt
	global_store_dwordx4 v[234:235], v[204:207], off offset:64 nt
	global_store_dwordx4 v[234:235], v[208:211], off offset:512 nt
	global_store_dwordx4 v[234:235], v[212:215], off offset:576 nt
	v_lshl_add_u64 v[234:235], v[240:241], 0, v[136:137]
	global_load_dwordx4 v[200:203], v[234:235], off nt
	global_load_dwordx4 v[204:207], v[234:235], off offset:64 nt
	global_load_dwordx4 v[208:211], v[234:235], off offset:512 nt
	global_load_dwordx4 v[212:215], v[234:235], off offset:576 nt
	s_waitcnt vmcnt(16)
	v_pk_fma_f32 v[216:217], v[98:99], v[158:159], v[216:217]
	v_pk_fma_f32 v[218:219], v[100:101], v[160:161], v[218:219]
	v_pk_fma_f32 v[220:221], v[90:91], v[162:163], v[220:221]
	v_pk_fma_f32 v[222:223], v[92:93], v[164:165], v[222:223]
	v_pk_fma_f32 v[224:225], v[86:87], v[166:167], v[224:225]
	v_pk_fma_f32 v[226:227], v[88:89], v[168:169], v[226:227]
	v_pk_fma_f32 v[228:229], v[82:83], v[170:171], v[228:229]
	v_pk_fma_f32 v[230:231], v[84:85], v[172:173], v[230:231]
	global_store_dwordx4 v[236:237], v[216:219], off nt
	global_store_dwordx4 v[236:237], v[220:223], off offset:64 nt
	global_store_dwordx4 v[236:237], v[224:227], off offset:512 nt
	global_store_dwordx4 v[236:237], v[228:231], off offset:576 nt
	v_lshl_add_u64 v[236:237], v[240:241], 0, v[138:139]
	global_load_dwordx4 v[216:219], v[236:237], off nt
	global_load_dwordx4 v[220:223], v[236:237], off offset:64 nt
	global_load_dwordx4 v[224:227], v[236:237], off offset:512 nt
	global_load_dwordx4 v[228:231], v[236:237], off offset:576 nt
	s_waitcnt vmcnt(16)
	v_pk_fma_f32 v[184:185], v[78:79], v[158:159], v[184:185]
	v_pk_fma_f32 v[186:187], v[80:81], v[160:161], v[186:187]
	v_pk_fma_f32 v[188:189], v[74:75], v[162:163], v[188:189]
	v_pk_fma_f32 v[190:191], v[76:77], v[164:165], v[190:191]
	v_pk_fma_f32 v[192:193], v[70:71], v[166:167], v[192:193]
	v_pk_fma_f32 v[194:195], v[72:73], v[168:169], v[194:195]
	v_pk_fma_f32 v[196:197], v[66:67], v[170:171], v[196:197]
	v_pk_fma_f32 v[198:199], v[68:69], v[172:173], v[198:199]
	global_store_dwordx4 v[232:233], v[184:187], off nt
	global_store_dwordx4 v[232:233], v[188:191], off offset:64 nt
	global_store_dwordx4 v[232:233], v[192:195], off offset:512 nt
	global_store_dwordx4 v[232:233], v[196:199], off offset:576 nt
	v_lshl_add_u64 v[232:233], v[240:241], 0, v[140:141]
	global_load_dwordx4 v[184:187], v[232:233], off nt
	global_load_dwordx4 v[188:191], v[232:233], off offset:64 nt
	global_load_dwordx4 v[192:195], v[232:233], off offset:512 nt
	global_load_dwordx4 v[196:199], v[232:233], off offset:576 nt
	s_waitcnt vmcnt(16)
	v_pk_fma_f32 v[200:201], v[62:63], v[158:159], v[200:201]
	v_pk_fma_f32 v[202:203], v[64:65], v[160:161], v[202:203]
	v_pk_fma_f32 v[204:205], v[58:59], v[162:163], v[204:205]
	v_pk_fma_f32 v[206:207], v[60:61], v[164:165], v[206:207]
	v_pk_fma_f32 v[208:209], v[54:55], v[166:167], v[208:209]
	v_pk_fma_f32 v[210:211], v[56:57], v[168:169], v[210:211]
	v_pk_fma_f32 v[212:213], v[50:51], v[170:171], v[212:213]
	v_pk_fma_f32 v[214:215], v[52:53], v[172:173], v[214:215]
	global_store_dwordx4 v[234:235], v[200:203], off nt
	global_store_dwordx4 v[234:235], v[204:207], off offset:64 nt
	global_store_dwordx4 v[234:235], v[208:211], off offset:512 nt
	global_store_dwordx4 v[234:235], v[212:215], off offset:576 nt
	v_lshl_add_u64 v[234:235], v[240:241], 0, v[142:143]
	global_load_dwordx4 v[200:203], v[234:235], off nt
	global_load_dwordx4 v[204:207], v[234:235], off offset:64 nt
	global_load_dwordx4 v[208:211], v[234:235], off offset:512 nt
	global_load_dwordx4 v[212:215], v[234:235], off offset:576 nt
	s_waitcnt vmcnt(16)
	v_pk_fma_f32 v[216:217], v[46:47], v[158:159], v[216:217]
	v_pk_fma_f32 v[218:219], v[48:49], v[160:161], v[218:219]
	v_pk_fma_f32 v[220:221], v[42:43], v[162:163], v[220:221]
	v_pk_fma_f32 v[222:223], v[44:45], v[164:165], v[222:223]
	v_pk_fma_f32 v[224:225], v[38:39], v[166:167], v[224:225]
	v_pk_fma_f32 v[226:227], v[40:41], v[168:169], v[226:227]
	v_pk_fma_f32 v[228:229], v[30:31], v[170:171], v[228:229]
	v_pk_fma_f32 v[230:231], v[32:33], v[172:173], v[230:231]
	global_store_dwordx4 v[236:237], v[216:219], off nt
	global_store_dwordx4 v[236:237], v[220:223], off offset:64 nt
	global_store_dwordx4 v[236:237], v[224:227], off offset:512 nt
	global_store_dwordx4 v[236:237], v[228:231], off offset:576 nt
	s_waitcnt vmcnt(12)
	v_pk_fma_f32 v[184:185], v[34:35], v[158:159], v[184:185]
	v_pk_fma_f32 v[186:187], v[36:37], v[160:161], v[186:187]
	v_pk_fma_f32 v[188:189], v[26:27], v[162:163], v[188:189]
	v_pk_fma_f32 v[190:191], v[28:29], v[164:165], v[190:191]
	v_pk_fma_f32 v[192:193], v[22:23], v[166:167], v[192:193]
	v_pk_fma_f32 v[194:195], v[24:25], v[168:169], v[194:195]
	v_pk_fma_f32 v[196:197], v[14:15], v[170:171], v[196:197]
	v_pk_fma_f32 v[198:199], v[16:17], v[172:173], v[198:199]
	global_store_dwordx4 v[232:233], v[184:187], off nt
	global_store_dwordx4 v[232:233], v[188:191], off offset:64 nt
	global_store_dwordx4 v[232:233], v[192:195], off offset:512 nt
	global_store_dwordx4 v[232:233], v[196:199], off offset:576 nt
	s_waitcnt vmcnt(8)
	v_pk_fma_f32 v[200:201], v[18:19], v[158:159], v[200:201]
	v_pk_fma_f32 v[202:203], v[20:21], v[160:161], v[202:203]
	v_pk_fma_f32 v[204:205], v[10:11], v[162:163], v[204:205]
	v_pk_fma_f32 v[206:207], v[12:13], v[164:165], v[206:207]
	v_pk_fma_f32 v[208:209], v[6:7], v[166:167], v[208:209]
	v_pk_fma_f32 v[210:211], v[8:9], v[168:169], v[210:211]
	v_pk_fma_f32 v[212:213], v[2:3], v[170:171], v[212:213]
	v_pk_fma_f32 v[214:215], v[4:5], v[172:173], v[214:215]
	global_store_dwordx4 v[234:235], v[200:203], off nt
	global_store_dwordx4 v[234:235], v[204:207], off offset:64 nt
	global_store_dwordx4 v[234:235], v[208:211], off offset:512 nt
	global_store_dwordx4 v[234:235], v[212:215], off offset:576 nt
	s_mov_b64 s[16:17], -1
	s_and_b64 vcc, exec, s[4:5]
	s_cbranch_vccnz .LBB0_2571
	s_andn2_b64 vcc, exec, s[8:9]
	s_cbranch_vccnz .LBB0_2570
	s_barrier
	s_branch .LBB0_2570
